# attention PV: V fragment reads as two conflict-free ds_read_b64 from one base instead of 2-way-conflicted ds_read2_b64
# speedup vs baseline: 1.0075x; 1.0026x over previous
; #define LAS __attribute__((address_space(3)))
; __device__ __forceinline__ unsigned pk2(float lo, float hi) { const f32x2 v = {lo, hi}; const bf16x2_t b = __builtin_convertvector(v, bf16x2_t); return __builtin_bit_cast(unsigned, b); }
; __device__ __forceinline__ void attn_unit(Frame& F, int b, int h, int qt, int kb_lo, int nkb, const bf16* QB, const bf16* KB, const bf16* VT, bf16* OUT, float bias2, f32x4* part, float* tpart) {
;     ...
;             const float Y3 = carry, Y2 = Y3 * GT[3], Y1 = Y2 * GT[2], Y0 = Y1 * GT[1];
;             carry = Y0 * GT[0];
;             const float f[4] = {Y0 * X[0], Y1 * X[1], Y2 * X[2], Y3 * X[3]};
;             bf16x8 pf[2];
; #pragma unroll
;             for (int ks = 0; ks < 2; ++ks) { u32x4 pw; pw.x = pk2(bt[2 * ks][0] * f[2 * ks], bt[2 * ks][1] * f[2 * ks]); pw.y = pk2(bt[2 * ks][2] * f[2 * ks], bt[2 * ks][3] * f[2 * ks]);
;                 pw.z = pk2(bt[2 * ks + 1][0] * f[2 * ks + 1], bt[2 * ks + 1][1] * f[2 * ks + 1]); pw.w = pk2(bt[2 * ks + 1][2] * f[2 * ks + 1], bt[2 * ks + 1][3] * f[2 * ks + 1]); pf[ks] = __builtin_bit_cast(bf16x8, pw); }
; #pragma unroll
;             for (int dt = 0; dt < 8; ++dt)
; #pragma unroll
;                 for (int ks = 0; ks < 2; ++ks) { const LAS bf16* vp = Vb + (16 * dt + li) * 72 + 32 * ks + 4 * g;
;                     const u32x2 a0 = *(const LAS u32x2*)vp, a1 = *(const LAS u32x2*)(vp + 16); const u32x4 av = (u32x4){a0.x, a0.y, a1.x, a1.y};
;                     oacc[dt] = __builtin_amdgcn_mfma_f32_16x16x32_bf16(__builtin_bit_cast(bf16x8, av), pf[ks], oacc[dt], 0, 0, 0); }
.LBB0_1058:
	s_or_b64 exec, exec, s[4:5]
	s_waitcnt lgkmcnt(5)
	v_mul_f32_e32 v137, v140, v141
	v_pk_mul_f32 v[140:141], v[104:105], v[100:101]
	s_waitcnt lgkmcnt(2)
	v_mul_f32_e32 v101, v102, v131
	s_waitcnt lgkmcnt(1)
	v_mul_f32_e32 v101, v101, v135
	v_mul_f32_e32 v137, v137, v142
	v_mul_f32_e32 v100, v133, v134
	s_waitcnt lgkmcnt(0)
	v_mul_f32_e32 v101, v101, v136
	v_mul_f32_e32 v137, v137, v143
	v_mul_f32_e32 v100, v100, v138
	v_mul_f32_e32 v101, v81, v101
	v_mul_f32_e32 v100, v100, v139
	v_mul_f32_e32 v102, v137, v101
	v_pk_mul_f32 v[92:93], v[108:109], v[92:93]
	v_mul_f32_e32 v109, v100, v102
	v_mul_f32_e32 v88, v127, v88
	v_pk_mul_f32 v[86:87], v[110:111], v[86:87]
	s_mul_i32 s4, s27, 0x4800
	v_mul_f32_e32 v100, v116, v109
	v_mul_f32_e32 v104, v117, v102
	v_mul_f32_e32 v108, v81, v103
	v_pk_mul_f32 v[86:87], v[86:87], v[100:101] op_sel_hi:[1,0]
	v_pk_mul_f32 v[88:89], v[88:89], v[100:101] op_sel_hi:[1,0]
	v_add3_u32 v81, v77, s4, v73
	ds_read_b64 v[184:185], v81 offset:34816
	ds_read_b64 v[186:187], v81 offset:34848
	ds_read_b64 v[188:189], v81 offset:34880
	ds_read_b64 v[190:191], v81 offset:34912
	ds_read_b64 v[192:193], v81 offset:37120
	ds_read_b64 v[194:195], v81 offset:37152
	ds_read_b64 v[196:197], v81 offset:37184
	ds_read_b64 v[198:199], v81 offset:37216
	ds_read_b64 v[200:201], v81 offset:39424
	ds_read_b64 v[202:203], v81 offset:39456
	ds_read_b64 v[204:205], v81 offset:39488
	ds_read_b64 v[206:207], v81 offset:39520
	v_cvt_pk_bf16_f32 v86, v86, v87
	v_cvt_pk_bf16_f32 v87, v88, v89
	v_pk_mul_f32 v[88:89], v[92:93], v[104:105] op_sel_hi:[1,0]
	v_pk_mul_f32 v[96:97], v[106:107], v[96:97]
	v_mul_f32_e32 v106, v132, v101
	v_mul_f32_e32 v90, v128, v90
	v_pk_mul_f32 v[90:91], v[90:91], v[104:105] op_sel_hi:[1,0]
	v_cvt_pk_bf16_f32 v88, v88, v89
	v_cvt_pk_bf16_f32 v89, v90, v91
	v_mul_f32_e32 v94, v129, v94
	v_pk_mul_f32 v[94:95], v[94:95], v[106:107] op_sel_hi:[1,0]
	s_nop 0
	s_waitcnt lgkmcnt(10)
	v_mfma_f32_16x16x32_bf16 v[30:33], v[184:187], v[86:89], v[30:33]
	ds_read_b64 v[184:185], v81 offset:41728
	ds_read_b64 v[186:187], v81 offset:41760
	v_mul_f32_e32 v98, v130, v98
	v_cvt_pk_bf16_f32 v105, v94, v95
	v_pk_mul_f32 v[94:95], v[140:141], v[108:109] op_sel_hi:[1,0]
	v_pk_mul_f32 v[96:97], v[96:97], v[106:107] op_sel_hi:[1,0]
	v_cvt_pk_bf16_f32 v106, v94, v95
	v_pk_mul_f32 v[94:95], v[98:99], v[108:109] op_sel_hi:[1,0]
	v_cvt_pk_bf16_f32 v104, v96, v97
	v_cvt_pk_bf16_f32 v107, v94, v95
	s_nop 1
	s_waitcnt lgkmcnt(10)
	v_mfma_f32_16x16x32_bf16 v[30:33], v[188:191], v[104:107], v[30:33]
	ds_read_b64 v[188:189], v81 offset:41792
	ds_read_b64 v[190:191], v81 offset:41824
	s_waitcnt lgkmcnt(8)
	v_mfma_f32_16x16x32_bf16 v[26:29], v[192:195], v[86:89], v[26:29]
	ds_read_b64 v[192:193], v81 offset:44032
	ds_read_b64 v[194:195], v81 offset:44064
	v_mfma_f32_16x16x32_bf16 v[26:29], v[196:199], v[104:107], v[26:29]
	ds_read_b64 v[196:197], v81 offset:44096
	ds_read_b64 v[198:199], v81 offset:44128
	s_waitcnt lgkmcnt(8)
	v_mfma_f32_16x16x32_bf16 v[22:25], v[200:203], v[86:89], v[22:25]
	ds_read_b64 v[200:201], v81 offset:46336
	ds_read_b64 v[202:203], v81 offset:46368
	v_mfma_f32_16x16x32_bf16 v[22:25], v[204:207], v[104:107], v[22:25]
	ds_read_b64 v[204:205], v81 offset:46400
	ds_read_b64 v[206:207], v81 offset:46432
	s_waitcnt lgkmcnt(8)
	v_mfma_f32_16x16x32_bf16 v[18:21], v[184:187], v[86:89], v[18:21]
	ds_read_b64 v[184:185], v81 offset:48640
	ds_read_b64 v[186:187], v81 offset:48672
	v_mfma_f32_16x16x32_bf16 v[18:21], v[188:191], v[104:107], v[18:21]
	ds_read_b64 v[188:189], v81 offset:48704
	ds_read_b64 v[190:191], v81 offset:48736
	s_waitcnt lgkmcnt(8)
	v_mfma_f32_16x16x32_bf16 v[14:17], v[192:195], v[86:89], v[14:17]
	ds_read_b64 v[192:193], v81 offset:50944
	ds_read_b64 v[194:195], v81 offset:50976
	v_mfma_f32_16x16x32_bf16 v[14:17], v[196:199], v[104:107], v[14:17]
	ds_read_b64 v[196:197], v81 offset:51008
	ds_read_b64 v[198:199], v81 offset:51040
	s_waitcnt lgkmcnt(8)
	v_mfma_f32_16x16x32_bf16 v[10:13], v[200:203], v[86:89], v[10:13]
	v_mfma_f32_16x16x32_bf16 v[10:13], v[204:207], v[104:107], v[10:13]
	s_waitcnt lgkmcnt(4)
	v_mfma_f32_16x16x32_bf16 v[6:9], v[184:187], v[86:89], v[6:9]
	v_mfma_f32_16x16x32_bf16 v[6:9], v[188:191], v[104:107], v[6:9]
	v_mul_f32_e32 v81, v112, v113
	v_mul_f32_e32 v81, v81, v114
	s_waitcnt lgkmcnt(2)
	v_mfma_f32_16x16x32_bf16 v[2:5], v[192:195], v[86:89], v[2:5]
	v_mul_f32_e32 v81, v81, v115
	v_mul_f32_e32 v81, v81, v109
	s_waitcnt lgkmcnt(0)
	v_mfma_f32_16x16x32_bf16 v[2:5], v[196:199], v[104:107], v[2:5]
